# RWKV producers publish (L2 write-back + flag) only after rounds 3, 7 and the last one instead of every round
# speedup vs baseline: 1.0704x; 1.0194x over previous
; DEVINL void rw_project_head(const Ctx& c, int layer, int b, int hd, int pj, int nP, unsigned* cnt, unsigned char* lds) {
;     ...
;         asm volatile("s_waitcnt vmcnt(0)" ::: "memory");
;         __syncthreads();
;         if (threadIdx.x == 0) {
;             __builtin_amdgcn_fence(__ATOMIC_RELEASE, "agent");
;             __hip_atomic_store(cnt, (unsigned)(layer * 16 + round + 1), __ATOMIC_RELAXED, __HIP_MEMORY_SCOPE_AGENT);
;         }
.LBB0_237:
	s_or_b64 exec, exec, s[12:13]
	s_waitcnt vmcnt(0)
	s_waitcnt vmcnt(63) expcnt(7) lgkmcnt(15)
	s_barrier
	s_mov_b64 s[0:1], exec
	v_cmp_eq_u32_e32 vcc, 0x1c0, v160
	s_nop 0
	s_and_b64 s[12:13], s[0:1], vcc
	s_mov_b64 exec, s[12:13]
	s_cbranch_execz .LBB0_140
	s_add_i32 s12, s16, s20
	s_cmp_lt_u32 s12, s17
	s_cbranch_scc0 .Lpub_do
	s_sub_i32 s13, s19, 1
	s_and_b32 s13, s13, 15
	s_movk_i32 s12, 0x88
	s_movk_i32 s14, 0x8
	s_cmp_eq_u32 s30, 3
	s_cselect_b32 s12, s14, s12
	s_bitcmp1_b32 s12, s13
	s_cbranch_scc0 .LBB0_140
.Lpub_do:
	v_mov_b32_e32 v0, s19
	buffer_wbl2 sc1
	s_waitcnt vmcnt(0)
	global_store_dword v65, v0, s[8:9] sc1
	s_branch .LBB0_140
